# grid barriers: pipelined polling (4 sc1 loads in flight) at the 10 inter-phase barriers
# baseline (speedup 1.0000x reference)
.LBB0_171:
	global_load_dword v1, v0, s[74:75] offset:512 sc1
	s_sleep 3
	global_load_dword v4, v0, s[74:75] offset:512 sc1
	s_sleep 3
	global_load_dword v5, v0, s[74:75] offset:512 sc1
	s_sleep 3
	global_load_dword v6, v0, s[74:75] offset:512 sc1
.Lpb0_spin:
	s_waitcnt vmcnt(3)
	v_cmp_le_u32_e32 vcc, s92, v1
	s_cbranch_vccnz .LBB0_172
	global_load_dword v1, v0, s[74:75] offset:512 sc1
	s_waitcnt vmcnt(3)
	v_cmp_le_u32_e32 vcc, s92, v4
	s_cbranch_vccnz .LBB0_172
	global_load_dword v4, v0, s[74:75] offset:512 sc1
	s_waitcnt vmcnt(3)
	v_cmp_le_u32_e32 vcc, s92, v5
	s_cbranch_vccnz .LBB0_172
	global_load_dword v5, v0, s[74:75] offset:512 sc1
	s_waitcnt vmcnt(3)
	v_cmp_le_u32_e32 vcc, s92, v6
	s_cbranch_vccnz .LBB0_172
	global_load_dword v6, v0, s[74:75] offset:512 sc1
	s_branch .Lpb0_spin

.LBB0_354:
	global_load_dword v1, v0, s[74:75] offset:1024 sc1
	s_sleep 3
	global_load_dword v4, v0, s[74:75] offset:1024 sc1
	s_sleep 3
	global_load_dword v5, v0, s[74:75] offset:1024 sc1
	s_sleep 3
	global_load_dword v6, v0, s[74:75] offset:1024 sc1
.Lpb1_spin:
	s_waitcnt vmcnt(3)
	v_cmp_le_u32_e32 vcc, s92, v1
	s_cbranch_vccnz .LBB0_355
	global_load_dword v1, v0, s[74:75] offset:1024 sc1
	s_waitcnt vmcnt(3)
	v_cmp_le_u32_e32 vcc, s92, v4
	s_cbranch_vccnz .LBB0_355
	global_load_dword v4, v0, s[74:75] offset:1024 sc1
	s_waitcnt vmcnt(3)
	v_cmp_le_u32_e32 vcc, s92, v5
	s_cbranch_vccnz .LBB0_355
	global_load_dword v5, v0, s[74:75] offset:1024 sc1
	s_waitcnt vmcnt(3)
	v_cmp_le_u32_e32 vcc, s92, v6
	s_cbranch_vccnz .LBB0_355
	global_load_dword v6, v0, s[74:75] offset:1024 sc1
	s_branch .Lpb1_spin

.LBB0_573:
	global_load_dword v1, v0, s[74:75] offset:1536 sc1
	s_sleep 3
	global_load_dword v4, v0, s[74:75] offset:1536 sc1
	s_sleep 3
	global_load_dword v5, v0, s[74:75] offset:1536 sc1
	s_sleep 3
	global_load_dword v6, v0, s[74:75] offset:1536 sc1
.Lpb2_spin:
	s_waitcnt vmcnt(3)
	v_cmp_le_u32_e32 vcc, s92, v1
	s_cbranch_vccnz .LBB0_574
	global_load_dword v1, v0, s[74:75] offset:1536 sc1
	s_waitcnt vmcnt(3)
	v_cmp_le_u32_e32 vcc, s92, v4
	s_cbranch_vccnz .LBB0_574
	global_load_dword v4, v0, s[74:75] offset:1536 sc1
	s_waitcnt vmcnt(3)
	v_cmp_le_u32_e32 vcc, s92, v5
	s_cbranch_vccnz .LBB0_574
	global_load_dword v5, v0, s[74:75] offset:1536 sc1
	s_waitcnt vmcnt(3)
	v_cmp_le_u32_e32 vcc, s92, v6
	s_cbranch_vccnz .LBB0_574
	global_load_dword v6, v0, s[74:75] offset:1536 sc1
	s_branch .Lpb2_spin

.LBB0_708:
	global_load_dword v1, v0, s[74:75] offset:2560 sc1
	s_sleep 3
	global_load_dword v4, v0, s[74:75] offset:2560 sc1
	s_sleep 3
	global_load_dword v5, v0, s[74:75] offset:2560 sc1
	s_sleep 3
	global_load_dword v6, v0, s[74:75] offset:2560 sc1
.Lpb3_spin:
	s_waitcnt vmcnt(3)
	v_cmp_le_u32_e32 vcc, s92, v1
	s_cbranch_vccnz .LBB0_709
	global_load_dword v1, v0, s[74:75] offset:2560 sc1
	s_waitcnt vmcnt(3)
	v_cmp_le_u32_e32 vcc, s92, v4
	s_cbranch_vccnz .LBB0_709
	global_load_dword v4, v0, s[74:75] offset:2560 sc1
	s_waitcnt vmcnt(3)
	v_cmp_le_u32_e32 vcc, s92, v5
	s_cbranch_vccnz .LBB0_709
	global_load_dword v5, v0, s[74:75] offset:2560 sc1
	s_waitcnt vmcnt(3)
	v_cmp_le_u32_e32 vcc, s92, v6
	s_cbranch_vccnz .LBB0_709
	global_load_dword v6, v0, s[74:75] offset:2560 sc1
	s_branch .Lpb3_spin

.LBB0_742:
	global_load_dword v1, v0, s[74:75] offset:3072 sc1
	s_sleep 3
	global_load_dword v4, v0, s[74:75] offset:3072 sc1
	s_sleep 3
	global_load_dword v5, v0, s[74:75] offset:3072 sc1
	s_sleep 3
	global_load_dword v6, v0, s[74:75] offset:3072 sc1
.Lpb4_spin:
	s_waitcnt vmcnt(3)
	v_cmp_le_u32_e32 vcc, s92, v1
	s_cbranch_vccnz .LBB0_743
	global_load_dword v1, v0, s[74:75] offset:3072 sc1
	s_waitcnt vmcnt(3)
	v_cmp_le_u32_e32 vcc, s92, v4
	s_cbranch_vccnz .LBB0_743
	global_load_dword v4, v0, s[74:75] offset:3072 sc1
	s_waitcnt vmcnt(3)
	v_cmp_le_u32_e32 vcc, s92, v5
	s_cbranch_vccnz .LBB0_743
	global_load_dword v5, v0, s[74:75] offset:3072 sc1
	s_waitcnt vmcnt(3)
	v_cmp_le_u32_e32 vcc, s92, v6
	s_cbranch_vccnz .LBB0_743
	global_load_dword v6, v0, s[74:75] offset:3072 sc1
	s_branch .Lpb4_spin

.LBB0_820:
	global_load_dword v1, v0, s[74:75] offset:3584 sc1
	s_sleep 3
	global_load_dword v4, v0, s[74:75] offset:3584 sc1
	s_sleep 3
	global_load_dword v5, v0, s[74:75] offset:3584 sc1
	s_sleep 3
	global_load_dword v6, v0, s[74:75] offset:3584 sc1
.Lpb5_spin:
	s_waitcnt vmcnt(3)
	v_cmp_le_u32_e32 vcc, s92, v1
	s_cbranch_vccnz .LBB0_821
	global_load_dword v1, v0, s[74:75] offset:3584 sc1
	s_waitcnt vmcnt(3)
	v_cmp_le_u32_e32 vcc, s92, v4
	s_cbranch_vccnz .LBB0_821
	global_load_dword v4, v0, s[74:75] offset:3584 sc1
	s_waitcnt vmcnt(3)
	v_cmp_le_u32_e32 vcc, s92, v5
	s_cbranch_vccnz .LBB0_821
	global_load_dword v5, v0, s[74:75] offset:3584 sc1
	s_waitcnt vmcnt(3)
	v_cmp_le_u32_e32 vcc, s92, v6
	s_cbranch_vccnz .LBB0_821
	global_load_dword v6, v0, s[74:75] offset:3584 sc1
	s_branch .Lpb5_spin

.LBB0_880:
	global_load_dword v1, v0, s[2:3] sc1
	s_sleep 3
	global_load_dword v4, v0, s[2:3] sc1
	s_sleep 3
	global_load_dword v5, v0, s[2:3] sc1
	s_sleep 3
	global_load_dword v6, v0, s[2:3] sc1
.Lpb6_spin:
	s_waitcnt vmcnt(3)
	v_cmp_le_u32_e32 vcc, s92, v1
	s_cbranch_vccnz .LBB0_881
	global_load_dword v1, v0, s[2:3] sc1
	s_waitcnt vmcnt(3)
	v_cmp_le_u32_e32 vcc, s92, v4
	s_cbranch_vccnz .LBB0_881
	global_load_dword v4, v0, s[2:3] sc1
	s_waitcnt vmcnt(3)
	v_cmp_le_u32_e32 vcc, s92, v5
	s_cbranch_vccnz .LBB0_881
	global_load_dword v5, v0, s[2:3] sc1
	s_waitcnt vmcnt(3)
	v_cmp_le_u32_e32 vcc, s92, v6
	s_cbranch_vccnz .LBB0_881
	global_load_dword v6, v0, s[2:3] sc1
	s_branch .Lpb6_spin
